# attention work-queue ticket: atomic result wait deferred to the end of the unit (dedicated register) so its round trip overlaps the unit
# baseline (speedup 1.0000x reference)
; #define LAS __attribute__((address_space(3)))
; #define ATT_BAR() asm volatile("s_waitcnt lgkmcnt(0)\n\ts_barrier" ::: "memory")
; __device__ __forceinline__ void attn_unit(LAS unsigned char* lds, const bf16_t* Qrow0, int nqw, int limbase, bool prompt, size_t kv0, int NT, int h,
;                                           const bf16_t* KN, const bf16_t* KR, const bf16_t* VVt, bf16_t* Yrow0, unsigned* tkctr, int& tick) {
;     ...
;     float mrow = -1e30f, lsum = 0.f; f32x16 o0 = {}, o1 = {}, s0 = {}, s1 = {};
;     if (wid >= 4) __builtin_amdgcn_s_setprio(1);
;     const LAS unsigned char* kbase = lds + r32 * KPITCH + hi * 16;
;     const LAS unsigned char* vbase = lds + ATT_V0 + r32 * VPITCH + hi * 8;
;     if (lim > 0) attn_step<true, false>(kbase, vbase, qr, s0, s1, o0, o1, mrow, lsum);
;     ATT_BAR();
;     if (tkctr && tid == 0) tick = (int)atomicAdd(tkctr, 1u);
.LBB0_885:
	s_waitcnt lgkmcnt(0)
	s_barrier
	v_cmp_eq_u32_e32 vcc, 0, v34
	v_mov_b32_e32 v212, v209
	s_and_saveexec_b64 s[10:11], vcc
	s_cbranch_execz .LBB0_889
	s_mov_b64 s[64:65], exec
	v_mbcnt_lo_u32_b32 v0, s64, 0
	v_mbcnt_hi_u32_b32 v0, s65, v0
	v_cmp_eq_u32_e32 vcc, 0, v0
	s_and_saveexec_b64 s[62:63], vcc
	s_cbranch_execz .LBB0_888
	s_bcnt1_i32_b64 s40, s[64:65]
	v_mov_b32_e32 v2, s40
	global_atomic_add v236, v1, v2, s[38:39] sc0
.LBB0_888:
	s_or_b64 exec, exec, s[62:63]
.LBB0_889:
	s_or_b64 exec, exec, s[10:11]
	v_mov_b32_e32 v14, v1
	v_mov_b32_e32 v15, v1
	v_mad_i32_i24 v215, v35, s26, v32
	v_lshlrev_b32_e32 v204, 3, v36
	s_and_b64 s[10:11], s[60:61], exec
	v_mov_b32_e32 v0, v1
	v_mov_b32_e32 v2, v1
	v_mov_b32_e32 v3, v1
	v_mov_b32_e32 v4, v1
	v_mov_b32_e32 v5, v1
	v_mov_b32_e32 v6, v1
	v_mov_b32_e32 v7, v1
	v_mov_b32_e32 v8, v1
	v_mov_b32_e32 v9, v1
	v_mov_b32_e32 v10, v1
	v_mov_b32_e32 v11, v1
	v_mov_b32_e32 v12, v1
	v_mov_b32_e32 v13, v1
	v_mov_b64_e32 v[46:47], v[14:15]
	v_mov_b64_e32 v[78:79], v[14:15]
	s_mov_b32 s65, 0
	s_cselect_b32 s64, 33, 0
	v_mov_b32_e32 v206, 0xf149f2ca
	v_mov_b32_e32 v216, 0
	v_mov_b64_e32 v[44:45], v[12:13]
	v_mov_b64_e32 v[42:43], v[10:11]
	v_mov_b64_e32 v[40:41], v[8:9]
	v_mov_b64_e32 v[38:39], v[6:7]
	v_mov_b64_e32 v[36:37], v[4:5]
	v_mov_b64_e32 v[34:35], v[2:3]
	v_mov_b64_e32 v[32:33], v[0:1]
	v_mov_b64_e32 v[76:77], v[12:13]
	v_mov_b64_e32 v[74:75], v[10:11]
	v_mov_b64_e32 v[72:73], v[8:9]
	v_mov_b64_e32 v[70:71], v[6:7]
	v_mov_b64_e32 v[68:69], v[4:5]
	v_mov_b64_e32 v[66:67], v[2:3]
	v_mov_b64_e32 v[64:65], v[0:1]

; __device__ __forceinline__ unsigned cvt_pk_bf16(float lo, float hi) { unsigned r; asm("v_cvt_pk_bf16_f32 %0, %1, %2" : "=v"(r) : "v"(lo), "v"(hi)); return r; }
; __device__ __forceinline__ void attn_unit(LAS unsigned char* lds, const bf16_t* Qrow0, int nqw, int limbase, bool prompt, size_t kv0, int NT, int h,
;                                           const bf16_t* KN, const bf16_t* KR, const bf16_t* VVt, bf16_t* Yrow0, unsigned* tkctr, int& tick) {
;     ...
;     asm volatile("s_waitcnt vmcnt(0)" ::: "memory");
;     __builtin_amdgcn_s_setprio(0);
;     ...
;     if (wid < nqw) {
;         lsum += __shfl_xor(lsum, 32);
;         const float inv = 1.f / lsum;
;         bf16_t* yp = Yrow0 + (size_t)(wid * 32 + r32) * DM + 512 + h * 64 + 4 * hi;
; #pragma unroll
;         for (int g = 0; g < 4; ++g) {
;             u32x2 w; w.x = cvt_pk_bf16(o0[4 * g] * inv, o0[4 * g + 1] * inv); w.y = cvt_pk_bf16(o0[4 * g + 2] * inv, o0[4 * g + 3] * inv);
;             *(u32x2*)(yp + 8 * g) = w;
;             u32x2 x; x.x = cvt_pk_bf16(o1[4 * g] * inv, o1[4 * g + 1] * inv); x.y = cvt_pk_bf16(o1[4 * g + 2] * inv, o1[4 * g + 3] * inv);
;             *(u32x2*)(yp + 32 + 8 * g) = x; }
.LBB0_910:
	s_waitcnt vmcnt(0)
	v_mov_b32_e32 v212, v236
	s_setprio 0
	s_mov_b64 s[0:1], 0
	s_and_b64 vcc, exec, s[60:61]
	s_mov_b64 s[60:61], 0
	s_cbranch_vccz .LBB0_912
	v_and_b32_e32 v2, 64, v210
	v_xor_b32_e32 v0, 32, v210
	v_add_u32_e32 v2, 64, v2
	v_cmp_lt_i32_e32 vcc, v0, v2
	v_ashrrev_i32_e32 v199, 31, v198
	v_mov_b32_e32 v197, v1
	v_cndmask_b32_e32 v0, v210, v0, vcc
	v_lshlrev_b32_e32 v0, 2, v0
	ds_bpermute_b32 v0, v0, v216
	v_mov_b32_e32 v205, v1
	s_mov_b64 s[60:61], -1
	s_waitcnt lgkmcnt(0)
	v_add_f32_e32 v0, v216, v0
	v_div_scale_f32 v2, s[10:11], v0, v0, 1.0
	v_rcp_f32_e32 v3, v2
	v_div_scale_f32 v4, vcc, 1.0, v0, 1.0
	v_fma_f32 v5, -v2, v3, 1.0
	v_fmac_f32_e32 v3, v5, v3
	v_mul_f32_e32 v5, v4, v3
	v_fma_f32 v6, -v2, v5, v4
	v_fmac_f32_e32 v5, v6, v3
	v_fma_f32 v2, -v2, v5, v4
	v_div_fmas_f32 v2, v2, v3, v5
	v_div_fixup_f32 v0, v2, v0, 1.0
	v_lshlrev_b64 v[2:3], 11, v[198:199]
	v_lshl_add_u64 v[2:3], s[50:51], 0, v[2:3]
	v_mul_f32_e32 v6, v32, v0
	v_mul_f32_e32 v7, v33, v0
	v_lshl_add_u64 v[2:3], v[196:197], 1, v[2:3]
	v_cvt_pk_bf16_f32 v6, v6, v7
	v_mul_f32_e32 v7, v34, v0
	v_lshl_add_u64 v[4:5], v[2:3], 0, v[204:205]
	v_mul_f32_e32 v8, v35, v0
	v_cvt_pk_bf16_f32 v7, v7, v8
	global_store_dwordx2 v[4:5], v[6:7], off offset:1024
	v_mul_f32_e32 v6, v64, v0
	v_mul_f32_e32 v7, v65, v0
	v_cvt_pk_bf16_f32 v6, v6, v7
	v_mul_f32_e32 v7, v66, v0
	v_mul_f32_e32 v8, v67, v0
	v_cvt_pk_bf16_f32 v7, v7, v8
	global_store_dwordx2 v[4:5], v[6:7], off offset:1088
	v_mul_f32_e32 v6, v36, v0
	v_mul_f32_e32 v7, v37, v0
	v_cvt_pk_bf16_f32 v6, v6, v7
	v_mul_f32_e32 v7, v38, v0
	v_mul_f32_e32 v8, v39, v0
	v_cvt_pk_bf16_f32 v7, v7, v8
	global_store_dwordx2 v[4:5], v[6:7], off offset:1040
	v_mul_f32_e32 v6, v68, v0
	v_mul_f32_e32 v7, v69, v0
	v_cvt_pk_bf16_f32 v6, v6, v7
	v_mul_f32_e32 v7, v70, v0
	v_mul_f32_e32 v8, v71, v0
	v_cvt_pk_bf16_f32 v7, v7, v8
	global_store_dwordx2 v[4:5], v[6:7], off offset:1104
	v_mul_f32_e32 v6, v40, v0
	v_mul_f32_e32 v7, v41, v0
	v_cvt_pk_bf16_f32 v6, v6, v7
	v_mul_f32_e32 v7, v42, v0
	v_mul_f32_e32 v8, v43, v0
	v_cvt_pk_bf16_f32 v7, v7, v8
	global_store_dwordx2 v[4:5], v[6:7], off offset:1056
	v_mul_f32_e32 v6, v72, v0
	v_mul_f32_e32 v7, v73, v0
	v_cvt_pk_bf16_f32 v6, v6, v7
	v_mul_f32_e32 v7, v74, v0
	v_mul_f32_e32 v8, v75, v0
	v_cvt_pk_bf16_f32 v7, v7, v8
	global_store_dwordx2 v[4:5], v[6:7], off offset:1120
	v_mul_f32_e32 v6, v44, v0
	v_mul_f32_e32 v7, v45, v0
	v_cvt_pk_bf16_f32 v6, v6, v7
	v_mul_f32_e32 v7, v46, v0
	v_lshl_add_u64 v[2:3], v[4:5], 0, s[58:59]
	v_mul_f32_e32 v8, v47, v0
	v_cvt_pk_bf16_f32 v7, v7, v8
	global_store_dwordx2 v[4:5], v[6:7], off offset:1072
	v_mul_f32_e32 v4, v76, v0
	v_mul_f32_e32 v5, v77, v0
	v_cvt_pk_bf16_f32 v4, v4, v5
	v_mul_f32_e32 v5, v78, v0
	v_mul_f32_e32 v0, v79, v0
	v_cvt_pk_bf16_f32 v5, v5, v0

; #define LAS __attribute__((address_space(3)))
; #define ATT_BAR() asm volatile("s_waitcnt lgkmcnt(0)\n\ts_barrier" ::: "memory")
; __device__ __forceinline__ void attn_unit(LAS unsigned char* lds, const bf16_t* Qrow0, int nqw, int limbase, bool prompt, size_t kv0, int NT, int h,
;                                           const bf16_t* KN, const bf16_t* KR, const bf16_t* VVt, bf16_t* Yrow0, unsigned* tkctr, int& tick) {
;     ...
;     float mrow = -1e30f, lsum = 0.f; f32x16 o0 = {}, o1 = {}, s0 = {}, s1 = {};
;     if (wid >= 4) __builtin_amdgcn_s_setprio(1);
;     const LAS unsigned char* kbase = lds + r32 * KPITCH + hi * 16;
;     const LAS unsigned char* vbase = lds + ATT_V0 + r32 * VPITCH + hi * 8;
;     if (lim > 0) attn_step<true, false>(kbase, vbase, qr, s0, s1, o0, o1, mrow, lsum);
;     ATT_BAR();
;     if (tkctr && tid == 0) tick = (int)atomicAdd(tkctr, 1u);
.LBB0_934:
	s_waitcnt lgkmcnt(0)
	s_barrier
	v_cmp_eq_u32_e32 vcc, 0, v32
	s_and_saveexec_b64 s[10:11], vcc
	s_cbranch_execz .LBB0_938
	s_mov_b64 s[70:71], exec
	v_mbcnt_lo_u32_b32 v0, s70, 0
	v_mbcnt_hi_u32_b32 v0, s71, v0
	v_cmp_eq_u32_e32 vcc, 0, v0
	s_and_saveexec_b64 s[66:67], vcc
	s_cbranch_execz .LBB0_937
	s_bcnt1_i32_b64 s40, s[70:71]
	v_mov_b32_e32 v2, s40
	global_atomic_add v236, v1, v2, s[38:39] sc0
.LBB0_937:
	s_or_b64 exec, exec, s[66:67]
.LBB0_938:
	s_or_b64 exec, exec, s[10:11]
	s_cmp_lt_i32 s73, 0
	v_lshlrev_b32_e32 v204, 3, v34
	s_cbranch_scc1 .LBB0_959
	v_mov_b32_e32 v14, v1
	v_mov_b32_e32 v15, v1
	v_mad_i32_i24 v214, v33, s26, v35
	v_mov_b32_e32 v0, v1
	v_mov_b32_e32 v2, v1
	v_mov_b32_e32 v3, v1
	v_mov_b32_e32 v4, v1
	v_mov_b32_e32 v5, v1
	v_mov_b32_e32 v6, v1
	v_mov_b32_e32 v7, v1
	v_mov_b32_e32 v8, v1
	v_mov_b32_e32 v9, v1
	v_mov_b32_e32 v10, v1
	v_mov_b32_e32 v11, v1
	v_mov_b32_e32 v12, v1
	v_mov_b32_e32 v13, v1
	v_mov_b64_e32 v[46:47], v[14:15]
	v_mov_b64_e32 v[78:79], v[14:15]
	s_mov_b32 s73, 4
	s_add_i32 s74, s74, 4
	v_mov_b32_e32 v206, 0xf149f2ca
	v_mov_b32_e32 v215, 0
	v_mov_b64_e32 v[44:45], v[12:13]
	v_mov_b64_e32 v[42:43], v[10:11]
	v_mov_b64_e32 v[40:41], v[8:9]
	v_mov_b64_e32 v[38:39], v[6:7]
	v_mov_b64_e32 v[36:37], v[4:5]
	v_mov_b64_e32 v[34:35], v[2:3]
	v_mov_b64_e32 v[32:33], v[0:1]
	v_mov_b64_e32 v[76:77], v[12:13]
	v_mov_b64_e32 v[74:75], v[10:11]
	v_mov_b64_e32 v[72:73], v[8:9]
	v_mov_b64_e32 v[70:71], v[6:7]
	v_mov_b64_e32 v[68:69], v[4:5]
	v_mov_b64_e32 v[66:67], v[2:3]
	v_mov_b64_e32 v[64:65], v[0:1]
	v_mov_b32_e32 v218, 0
	v_mov_b32_e32 v219, 0
	v_mov_b32_e32 v220, 0
	v_mov_b32_e32 v221, 0
	v_mov_b32_e32 v222, 0
	v_mov_b32_e32 v223, 0
	v_mov_b32_e32 v224, 0
	v_mov_b32_e32 v225, 0
	v_mov_b32_e32 v226, 0
	v_mov_b32_e32 v227, 0
	v_mov_b32_e32 v228, 0
	v_mov_b32_e32 v229, 0
	v_mov_b32_e32 v230, 0
	v_mov_b32_e32 v231, 0
	v_mov_b32_e32 v232, 0
	v_mov_b32_e32 v233, 0
	s_mov_b32 s99, 0
	s_branch .LBB0_941

; __device__ __forceinline__ unsigned cvt_pk_bf16(float lo, float hi) { unsigned r; asm("v_cvt_pk_bf16_f32 %0, %1, %2" : "=v"(r) : "v"(lo), "v"(hi)); return r; }
; __device__ __forceinline__ void attn_unit(LAS unsigned char* lds, const bf16_t* Qrow0, int nqw, int limbase, bool prompt, size_t kv0, int NT, int h,
;                                           const bf16_t* KN, const bf16_t* KR, const bf16_t* VVt, bf16_t* Yrow0, unsigned* tkctr, int& tick) {
;     ...
;     asm volatile("s_waitcnt vmcnt(0)" ::: "memory");
;     __builtin_amdgcn_s_setprio(0);
;     ...
;     if (wid < nqw) {
;         lsum += __shfl_xor(lsum, 32);
;         const float inv = 1.f / lsum;
;         bf16_t* yp = Yrow0 + (size_t)(wid * 32 + r32) * DM + 512 + h * 64 + 4 * hi;
; #pragma unroll
;         for (int g = 0; g < 4; ++g) {
;             u32x2 w; w.x = cvt_pk_bf16(o0[4 * g] * inv, o0[4 * g + 1] * inv); w.y = cvt_pk_bf16(o0[4 * g + 2] * inv, o0[4 * g + 3] * inv);
;             *(u32x2*)(yp + 8 * g) = w;
;             u32x2 x; x.x = cvt_pk_bf16(o1[4 * g] * inv, o1[4 * g + 1] * inv); x.y = cvt_pk_bf16(o1[4 * g + 2] * inv, o1[4 * g + 3] * inv);
;             *(u32x2*)(yp + 32 + 8 * g) = x; }
.LBB0_960:
	s_waitcnt vmcnt(0)
	v_mov_b32_e32 v209, v236
	s_setprio 0
	s_and_b64 vcc, exec, s[64:65]
	s_cbranch_vccz .LBB0_962
	v_and_b32_e32 v2, 64, v210
	v_xor_b32_e32 v0, 32, v210
	v_add_u32_e32 v2, 64, v2
	v_cmp_lt_i32_e32 vcc, v0, v2
	v_ashrrev_i32_e32 v199, 31, v198
	v_mov_b32_e32 v195, v1
	v_cndmask_b32_e32 v0, v210, v0, vcc
	v_lshlrev_b32_e32 v0, 2, v0
	ds_bpermute_b32 v0, v0, v215
	v_mov_b32_e32 v205, v1
	s_mov_b64 s[60:61], -1
	s_waitcnt lgkmcnt(0)
	v_add_f32_e32 v0, v215, v0
	v_div_scale_f32 v2, s[0:1], v0, v0, 1.0
	v_rcp_f32_e32 v3, v2
	s_lshl_b64 s[0:1], s[62:63], 11
	s_add_u32 s0, s8, s0
	s_addc_u32 s1, s9, s1
	v_fma_f32 v4, -v2, v3, 1.0
	v_fmac_f32_e32 v3, v4, v3
	v_div_scale_f32 v4, vcc, 1.0, v0, 1.0
	v_mul_f32_e32 v5, v4, v3
	v_fma_f32 v6, -v2, v5, v4
	v_fmac_f32_e32 v5, v6, v3
	v_fma_f32 v2, -v2, v5, v4
	v_div_fmas_f32 v2, v2, v3, v5
	v_div_fixup_f32 v0, v2, v0, 1.0
	v_lshlrev_b64 v[2:3], 11, v[198:199]
	v_lshl_add_u64 v[2:3], s[0:1], 0, v[2:3]
	v_mul_f32_e32 v6, v32, v0
	v_mul_f32_e32 v7, v33, v0
	v_lshl_add_u64 v[2:3], v[194:195], 1, v[2:3]
	v_cvt_pk_bf16_f32 v6, v6, v7
	v_mul_f32_e32 v7, v34, v0
	v_lshl_add_u64 v[4:5], v[2:3], 0, v[204:205]
	v_mul_f32_e32 v8, v35, v0
	v_cvt_pk_bf16_f32 v7, v7, v8
	global_store_dwordx2 v[4:5], v[6:7], off offset:1024
	v_mul_f32_e32 v6, v64, v0
	v_mul_f32_e32 v7, v65, v0
	v_cvt_pk_bf16_f32 v6, v6, v7
	v_mul_f32_e32 v7, v66, v0
	v_mul_f32_e32 v8, v67, v0
	v_cvt_pk_bf16_f32 v7, v7, v8
	global_store_dwordx2 v[4:5], v[6:7], off offset:1088
	v_mul_f32_e32 v6, v36, v0
	v_mul_f32_e32 v7, v37, v0
	v_cvt_pk_bf16_f32 v6, v6, v7
	v_mul_f32_e32 v7, v38, v0
	v_mul_f32_e32 v8, v39, v0
	v_cvt_pk_bf16_f32 v7, v7, v8
	global_store_dwordx2 v[4:5], v[6:7], off offset:1040
	v_mul_f32_e32 v6, v68, v0
	v_mul_f32_e32 v7, v69, v0
	v_cvt_pk_bf16_f32 v6, v6, v7
	v_mul_f32_e32 v7, v70, v0
	v_mul_f32_e32 v8, v71, v0
	v_cvt_pk_bf16_f32 v7, v7, v8
	global_store_dwordx2 v[4:5], v[6:7], off offset:1104
	v_mul_f32_e32 v6, v40, v0
	v_mul_f32_e32 v7, v41, v0
	v_cvt_pk_bf16_f32 v6, v6, v7
	v_mul_f32_e32 v7, v42, v0
	v_mul_f32_e32 v8, v43, v0
	v_cvt_pk_bf16_f32 v7, v7, v8
	global_store_dwordx2 v[4:5], v[6:7], off offset:1056
	v_mul_f32_e32 v6, v72, v0
	v_mul_f32_e32 v7, v73, v0
	v_cvt_pk_bf16_f32 v6, v6, v7
	v_mul_f32_e32 v7, v74, v0
	v_mul_f32_e32 v8, v75, v0
	v_cvt_pk_bf16_f32 v7, v7, v8
	global_store_dwordx2 v[4:5], v[6:7], off offset:1120
	v_mul_f32_e32 v6, v44, v0
	v_mul_f32_e32 v7, v45, v0
	v_cvt_pk_bf16_f32 v6, v6, v7
	v_mul_f32_e32 v7, v46, v0
	v_lshl_add_u64 v[2:3], v[4:5], 0, s[58:59]
	v_mul_f32_e32 v8, v47, v0
	v_cvt_pk_bf16_f32 v7, v7, v8
	global_store_dwordx2 v[4:5], v[6:7], off offset:1072
	v_mul_f32_e32 v4, v76, v0
	v_mul_f32_e32 v5, v77, v0
	v_cvt_pk_bf16_f32 v4, v4, v5
	v_mul_f32_e32 v5, v78, v0
	v_mul_f32_e32 v0, v79, v0
	v_cvt_pk_bf16_f32 v5, v5, v0
